# strategy 7.2: out-proj and GLU epilogues wait per first consumer (counted vmcnt) instead of one vmcnt(0) after the tile loads; on top of v155
# speedup vs baseline: 1.0051x; 1.0050x over previous
; __device__ __forceinline__ float fsigmoid(float v) { return __builtin_amdgcn_rcpf(1.0f + __builtin_amdgcn_exp2f(-1.4426950408889634f * v)); }
; __device__ __forceinline__ u32x4 ldnt(const bf16_t* p) { return __builtin_nontemporal_load((const u32x4*)p); }
;     __device__ __forceinline__ void operator()(const f32x4 (&acc)[2][2][4][2], const Unit& u, int wr, int wc, int fr, int fq) const {
;     ...
; #pragma unroll
;         for (int ai = 0; ai < 2; ++ai)
; #pragma unroll
;             for (int m = 0; m < 4; ++m) sg[ai][m] = ldnt(proj + (size_t)(row0 + ai * HALF + m * 16) * 4096 + 3072 + colg);
;         asm volatile("" ::: "memory");
;         f32x4 t[2][4][2];
; #pragma unroll
;         for (int ai = 0; ai < 2; ++ai)
; #pragma unroll
;             for (int m = 0; m < 4; ++m)
; #pragma unroll
;                 for (int i = 0; i < 4; ++i) { t[ai][m][0][i] = acc[ai][0][m][0][i] * fsigmoid(acc[ai][1][m][0][i]); t[ai][m][1][i] = acc[ai][0][m][1][i] * fsigmoid(acc[ai][1][m][1][i]); }
.LBB0_453:
	v_mul_f32_e32 v124, 0xbfb8aa3b, v124
	v_exp_f32_e32 v124, v124
	v_mul_f32_e32 v116, 0xbfb8aa3b, v116
	v_exp_f32_e32 v198, v116
	v_mul_f32_e32 v116, 0xbfb8aa3b, v125
	v_add_f32_e32 v124, 1.0, v124
	v_exp_f32_e32 v125, v116
	v_mul_f32_e32 v117, 0xbfb8aa3b, v117
	v_rcp_f32_e32 v116, v124
	v_add_f32_e32 v124, 1.0, v198
	v_exp_f32_e32 v198, v117
	v_add_f32_e32 v125, 1.0, v125
	v_mul_f32_e32 v117, 0xbfb8aa3b, v126
	v_exp_f32_e32 v126, v117
	v_rcp_f32_e32 v117, v125
	v_add_f32_e32 v125, 1.0, v198
	v_rcp_f32_e32 v124, v124
	v_rcp_f32_e32 v125, v125
	v_mul_f32_e32 v104, 0xbfb8aa3b, v104
	v_exp_f32_e32 v104, v104
	v_mul_f32_e32 v96, 0xbfb8aa3b, v96
	v_pk_mul_f32 v[120:121], v[120:121], v[124:125]
	v_exp_f32_e32 v124, v96
	v_lshl_add_u32 v190, s0, 8, v192
	v_ashrrev_i32_e32 v191, 31, v190
	v_mul_f32_e32 v96, 0xbfb8aa3b, v105
	v_lshlrev_b64 v[112:113], 13, v[190:191]
	v_or_b32_e32 v188, 16, v190
	v_add_f32_e32 v104, 1.0, v104
	v_exp_f32_e32 v105, v96
	v_mul_f32_e32 v97, 0xbfb8aa3b, v97
	v_lshl_add_u64 v[112:113], s[8:9], 0, v[112:113]
	v_ashrrev_i32_e32 v189, 31, v188
	v_rcp_f32_e32 v96, v104
	v_add_f32_e32 v104, 1.0, v124
	v_exp_f32_e32 v124, v97
	v_lshl_add_u64 v[112:113], v[112:113], 0, v[168:169]
	v_lshlrev_b64 v[114:115], 13, v[188:189]
	v_add_co_u32_e32 v112, vcc, 0x1000, v112
	v_lshl_add_u64 v[114:115], s[8:9], 0, v[114:115]
	s_nop 0
	v_addc_co_u32_e32 v113, vcc, 0, v113, vcc
	v_lshl_add_u64 v[114:115], v[114:115], 0, v[168:169]
	v_add_f32_e32 v105, 1.0, v105
	v_mul_f32_e32 v97, 0xbfb8aa3b, v106
	v_add_co_u32_e32 v114, vcc, 0x1000, v114
	v_exp_f32_e32 v106, v97
	v_rcp_f32_e32 v97, v105
	v_add_f32_e32 v105, 1.0, v124
	v_addc_co_u32_e32 v115, vcc, 0, v115, vcc
	global_load_dwordx4 v[156:159], v[112:113], off offset:2048 nt
	global_load_dwordx4 v[152:155], v[114:115], off offset:2048 nt
	v_or_b32_e32 v186, 32, v190
	v_rcp_f32_e32 v104, v104
	v_rcp_f32_e32 v105, v105
	v_ashrrev_i32_e32 v187, 31, v186
	v_lshlrev_b64 v[112:113], 13, v[186:187]
	v_or_b32_e32 v184, 48, v190
	v_mul_f32_e32 v88, 0xbfb8aa3b, v88
	v_lshl_add_u64 v[112:113], s[8:9], 0, v[112:113]
	v_ashrrev_i32_e32 v185, 31, v184
	v_exp_f32_e32 v88, v88
	v_mul_f32_e32 v80, 0xbfb8aa3b, v80
	v_lshl_add_u64 v[112:113], v[112:113], 0, v[168:169]
	v_lshlrev_b64 v[114:115], 13, v[184:185]
	v_pk_mul_f32 v[100:101], v[100:101], v[104:105]
	v_exp_f32_e32 v104, v80
	v_add_co_u32_e32 v112, vcc, 0x1000, v112
	v_lshl_add_u64 v[114:115], s[8:9], 0, v[114:115]
	s_nop 0
	v_addc_co_u32_e32 v113, vcc, 0, v113, vcc
	v_lshl_add_u64 v[114:115], v[114:115], 0, v[168:169]
	v_mul_f32_e32 v80, 0xbfb8aa3b, v89
	v_add_co_u32_e32 v114, vcc, 0x1000, v114
	v_add_f32_e32 v88, 1.0, v88
	v_exp_f32_e32 v89, v80
	v_mul_f32_e32 v81, 0xbfb8aa3b, v81
	v_addc_co_u32_e32 v115, vcc, 0, v115, vcc
	global_load_dwordx4 v[148:151], v[112:113], off offset:2048 nt
	global_load_dwordx4 v[144:147], v[114:115], off offset:2048 nt
	v_add_u32_e32 v182, 0x80, v190
	v_rcp_f32_e32 v80, v88
	v_add_f32_e32 v88, 1.0, v104
	v_exp_f32_e32 v104, v81
	v_ashrrev_i32_e32 v183, 31, v182
	v_lshlrev_b64 v[112:113], 13, v[182:183]
	v_add_u32_e32 v180, 0x90, v190
	v_lshl_add_u64 v[112:113], s[8:9], 0, v[112:113]
	v_ashrrev_i32_e32 v181, 31, v180
	v_add_f32_e32 v89, 1.0, v89
	v_mul_f32_e32 v81, 0xbfb8aa3b, v90
	v_lshl_add_u64 v[112:113], v[112:113], 0, v[168:169]
	v_lshlrev_b64 v[114:115], 13, v[180:181]
	v_exp_f32_e32 v90, v81
	v_rcp_f32_e32 v81, v89
	v_add_f32_e32 v89, 1.0, v104
	v_add_co_u32_e32 v112, vcc, 0x1000, v112
	v_lshl_add_u64 v[114:115], s[8:9], 0, v[114:115]
	v_rcp_f32_e32 v88, v88
	v_rcp_f32_e32 v89, v89
	v_addc_co_u32_e32 v113, vcc, 0, v113, vcc
	v_lshl_add_u64 v[114:115], v[114:115], 0, v[168:169]
	v_add_co_u32_e32 v114, vcc, 0x1000, v114
	v_add_u32_e32 v178, 0xa0, v190
	v_mul_f32_e32 v72, 0xbfb8aa3b, v72
	v_addc_co_u32_e32 v115, vcc, 0, v115, vcc
	global_load_dwordx4 v[140:143], v[112:113], off offset:2048 nt
	global_load_dwordx4 v[136:139], v[114:115], off offset:2048 nt
	v_ashrrev_i32_e32 v179, 31, v178
	v_exp_f32_e32 v72, v72
	v_mul_f32_e32 v64, 0xbfb8aa3b, v64
	v_lshlrev_b64 v[112:113], 13, v[178:179]
	v_add_u32_e32 v176, 0xb0, v190
	v_pk_mul_f32 v[84:85], v[84:85], v[88:89]
	v_exp_f32_e32 v88, v64
	v_lshl_add_u64 v[112:113], s[8:9], 0, v[112:113]
	v_ashrrev_i32_e32 v177, 31, v176
	v_lshl_add_u64 v[112:113], v[112:113], 0, v[168:169]
	v_lshlrev_b64 v[114:115], 13, v[176:177]
	v_mul_f32_e32 v64, 0xbfb8aa3b, v73
	v_add_co_u32_e32 v112, vcc, 0x1000, v112
	v_lshl_add_u64 v[114:115], s[8:9], 0, v[114:115]
	v_add_f32_e32 v72, 1.0, v72
	v_exp_f32_e32 v73, v64
	v_mul_f32_e32 v65, 0xbfb8aa3b, v65
	v_addc_co_u32_e32 v113, vcc, 0, v113, vcc
	v_lshl_add_u64 v[114:115], v[114:115], 0, v[168:169]
	v_rcp_f32_e32 v64, v72
	v_add_f32_e32 v72, 1.0, v88
	v_exp_f32_e32 v88, v65
	v_add_co_u32_e32 v114, vcc, 0x1000, v114
	v_add_f32_e32 v73, 1.0, v73
	s_nop 0
	v_addc_co_u32_e32 v115, vcc, 0, v115, vcc
	global_load_dwordx4 v[132:135], v[112:113], off offset:2048 nt
	s_nop 0
	global_load_dwordx4 v[112:115], v[114:115], off offset:2048 nt
	v_mul_f32_e32 v65, 0xbfb8aa3b, v74
	v_exp_f32_e32 v74, v65
	v_rcp_f32_e32 v65, v73
	v_add_f32_e32 v73, 1.0, v88
	v_rcp_f32_e32 v72, v72
	v_rcp_f32_e32 v73, v73
	v_mul_f32_e32 v56, 0xbfb8aa3b, v56
	v_exp_f32_e32 v56, v56
	v_mul_f32_e32 v48, 0xbfb8aa3b, v48
	v_pk_mul_f32 v[68:69], v[68:69], v[72:73]
	v_exp_f32_e32 v72, v48
	v_mul_f32_e32 v48, 0xbfb8aa3b, v57
	v_add_f32_e32 v56, 1.0, v56
	v_exp_f32_e32 v57, v48
	v_mul_f32_e32 v49, 0xbfb8aa3b, v49
	v_rcp_f32_e32 v48, v56
	v_add_f32_e32 v56, 1.0, v72
	v_exp_f32_e32 v72, v49
	v_add_f32_e32 v57, 1.0, v57
	v_mul_f32_e32 v49, 0xbfb8aa3b, v58
	v_exp_f32_e32 v58, v49
; __device__ __forceinline__ float fsigmoid(float v) { return __builtin_amdgcn_rcpf(1.0f + __builtin_amdgcn_exp2f(-1.4426950408889634f * v)); }
;     __device__ __forceinline__ void operator()(const f32x4 (&acc)[2][2][4][2], const Unit& u, int wr, int wc, int fr, int fq) const {
;     ...
; #pragma unroll
;         for (int ai = 0; ai < 2; ++ai)
; #pragma unroll
;             for (int m = 0; m < 4; ++m)
; #pragma unroll
;                 for (int i = 0; i < 4; ++i) { t[ai][m][0][i] = acc[ai][0][m][0][i] * fsigmoid(acc[ai][1][m][0][i]); t[ai][m][1][i] = acc[ai][0][m][1][i] * fsigmoid(acc[ai][1][m][1][i]); }
;         asm volatile("" : "+v"(t[0][0][0]), "+v"(t[0][0][1]), "+v"(t[0][1][0]), "+v"(t[0][1][1]), "+v"(t[0][2][0]), "+v"(t[0][2][1]), "+v"(t[0][3][0]), "+v"(t[0][3][1]),
;                          "+v"(t[1][0][0]), "+v"(t[1][0][1]), "+v"(t[1][1][0]), "+v"(t[1][1][1]), "+v"(t[1][2][0]), "+v"(t[1][2][1]), "+v"(t[1][3][0]), "+v"(t[1][3][1]));
	v_rcp_f32_e32 v49, v57
	v_add_f32_e32 v57, 1.0, v72
	v_rcp_f32_e32 v56, v56
	v_rcp_f32_e32 v57, v57
	v_mul_f32_e32 v40, 0xbfb8aa3b, v40
	v_exp_f32_e32 v40, v40
	v_mul_f32_e32 v32, 0xbfb8aa3b, v32
	v_pk_mul_f32 v[52:53], v[52:53], v[56:57]
	v_exp_f32_e32 v56, v32
	v_mul_f32_e32 v32, 0xbfb8aa3b, v41
	v_add_f32_e32 v40, 1.0, v40
	v_exp_f32_e32 v41, v32
	v_mul_f32_e32 v33, 0xbfb8aa3b, v33
	v_rcp_f32_e32 v32, v40
	v_add_f32_e32 v40, 1.0, v56
	v_exp_f32_e32 v56, v33
	v_add_f32_e32 v41, 1.0, v41
	v_mul_f32_e32 v33, 0xbfb8aa3b, v42
	v_exp_f32_e32 v42, v33
	v_rcp_f32_e32 v33, v41
	v_add_f32_e32 v41, 1.0, v56
	v_rcp_f32_e32 v40, v40
	v_rcp_f32_e32 v41, v41
	v_mul_f32_e32 v24, 0xbfb8aa3b, v24
	v_exp_f32_e32 v24, v24
	v_mul_f32_e32 v16, 0xbfb8aa3b, v16
	v_pk_mul_f32 v[36:37], v[36:37], v[40:41]
	v_exp_f32_e32 v40, v16
	v_mul_f32_e32 v16, 0xbfb8aa3b, v25
	v_add_f32_e32 v24, 1.0, v24
	v_exp_f32_e32 v25, v16
	v_mul_f32_e32 v17, 0xbfb8aa3b, v17
	v_rcp_f32_e32 v16, v24
	v_add_f32_e32 v24, 1.0, v40
	v_exp_f32_e32 v40, v17
	v_add_f32_e32 v25, 1.0, v25
	v_mul_f32_e32 v17, 0xbfb8aa3b, v26
	v_mul_f32_e32 v127, 0xbfb8aa3b, v127
	v_mul_f32_e32 v107, 0xbfb8aa3b, v107
	v_mul_f32_e32 v91, 0xbfb8aa3b, v91
	v_mul_f32_e32 v75, 0xbfb8aa3b, v75
	v_mul_f32_e32 v59, 0xbfb8aa3b, v59
	v_mul_f32_e32 v43, 0xbfb8aa3b, v43
	v_exp_f32_e32 v26, v17
	v_rcp_f32_e32 v17, v25
	v_add_f32_e32 v25, 1.0, v40
	v_mul_f32_e32 v27, 0xbfb8aa3b, v27
	v_exp_f32_e32 v127, v127
	v_exp_f32_e32 v107, v107
	v_exp_f32_e32 v91, v91
	v_exp_f32_e32 v75, v75
	v_exp_f32_e32 v59, v59
	v_exp_f32_e32 v43, v43
	v_rcp_f32_e32 v24, v24
	v_rcp_f32_e32 v25, v25
	v_exp_f32_e32 v27, v27
	v_mul_f32_e32 v118, 0xbfb8aa3b, v118
	v_mul_f32_e32 v98, 0xbfb8aa3b, v98
	v_mul_f32_e32 v82, 0xbfb8aa3b, v82
	v_mul_f32_e32 v66, 0xbfb8aa3b, v66
	v_mul_f32_e32 v50, 0xbfb8aa3b, v50
	v_mul_f32_e32 v34, 0xbfb8aa3b, v34
	v_mul_f32_e32 v18, 0xbfb8aa3b, v18
	v_mul_f32_e32 v10, 0xbfb8aa3b, v10
	v_mul_f32_e32 v2, 0xbfb8aa3b, v2
	v_add_f32_e32 v126, 1.0, v126
	v_exp_f32_e32 v118, v118
	v_add_f32_e32 v127, 1.0, v127
	v_mul_f32_e32 v119, 0xbfb8aa3b, v119
	v_add_f32_e32 v106, 1.0, v106
	v_exp_f32_e32 v98, v98
	v_add_f32_e32 v107, 1.0, v107
	v_mul_f32_e32 v99, 0xbfb8aa3b, v99
	v_add_f32_e32 v90, 1.0, v90
	v_exp_f32_e32 v82, v82
	v_add_f32_e32 v91, 1.0, v91
	v_mul_f32_e32 v83, 0xbfb8aa3b, v83
	v_add_f32_e32 v74, 1.0, v74
	v_exp_f32_e32 v66, v66
	v_add_f32_e32 v75, 1.0, v75
	v_mul_f32_e32 v67, 0xbfb8aa3b, v67
	v_add_f32_e32 v58, 1.0, v58
	v_exp_f32_e32 v50, v50
	v_add_f32_e32 v59, 1.0, v59
	v_mul_f32_e32 v51, 0xbfb8aa3b, v51
	v_add_f32_e32 v42, 1.0, v42
	v_exp_f32_e32 v34, v34
	v_add_f32_e32 v43, 1.0, v43
	v_mul_f32_e32 v35, 0xbfb8aa3b, v35
	v_add_f32_e32 v26, 1.0, v26
	v_exp_f32_e32 v18, v18
	v_add_f32_e32 v27, 1.0, v27
	v_mul_f32_e32 v19, 0xbfb8aa3b, v19
	v_mul_f32_e32 v8, 0xbfb8aa3b, v8
	v_pk_mul_f32 v[20:21], v[20:21], v[24:25]
	v_mul_f32_e32 v0, 0xbfb8aa3b, v0
	v_mul_f32_e32 v9, 0xbfb8aa3b, v9
	v_mul_f32_e32 v1, 0xbfb8aa3b, v1
	v_exp_f32_e32 v10, v10
	v_exp_f32_e32 v24, v2
	v_mul_f32_e32 v11, 0xbfb8aa3b, v11
	v_mul_f32_e32 v3, 0xbfb8aa3b, v3
	v_rcp_f32_e32 v126, v126
	v_rcp_f32_e32 v127, v127
	v_exp_f32_e32 v199, v119
	v_rcp_f32_e32 v106, v106
	v_rcp_f32_e32 v107, v107
	v_exp_f32_e32 v125, v99
	v_rcp_f32_e32 v90, v90
	v_rcp_f32_e32 v91, v91
	v_exp_f32_e32 v105, v83
	v_rcp_f32_e32 v74, v74
	v_rcp_f32_e32 v75, v75
	v_exp_f32_e32 v89, v67
	v_rcp_f32_e32 v58, v58
	v_rcp_f32_e32 v59, v59
	v_exp_f32_e32 v73, v51
	v_rcp_f32_e32 v42, v42
	v_rcp_f32_e32 v43, v43
	v_exp_f32_e32 v57, v35
	v_rcp_f32_e32 v26, v26
	v_rcp_f32_e32 v27, v27
	v_exp_f32_e32 v41, v19
	v_exp_f32_e32 v8, v8
	v_exp_f32_e32 v0, v0
	v_exp_f32_e32 v9, v9
	v_exp_f32_e32 v1, v1
	v_exp_f32_e32 v11, v11
	v_exp_f32_e32 v25, v3
	v_add_f32_e32 v118, 1.0, v118
	v_add_f32_e32 v98, 1.0, v98
	v_add_f32_e32 v82, 1.0, v82
	v_add_f32_e32 v66, 1.0, v66
	v_add_f32_e32 v50, 1.0, v50
	v_add_f32_e32 v34, 1.0, v34
	v_add_f32_e32 v18, 1.0, v18
	v_add_f32_e32 v2, 1.0, v10
	v_add_f32_e32 v10, 1.0, v24
	v_rcp_f32_e32 v198, v118
	v_pk_mul_f32 v[118:119], v[130:131], v[126:127]
	v_add_f32_e32 v126, 1.0, v199
	v_rcp_f32_e32 v124, v98
	v_pk_mul_f32 v[98:99], v[110:111], v[106:107]
	v_add_f32_e32 v106, 1.0, v125
	v_rcp_f32_e32 v104, v82
	v_pk_mul_f32 v[82:83], v[94:95], v[90:91]
	v_add_f32_e32 v90, 1.0, v105
	v_rcp_f32_e32 v88, v66
	v_pk_mul_f32 v[66:67], v[78:79], v[74:75]
	v_add_f32_e32 v74, 1.0, v89
	v_rcp_f32_e32 v72, v50
	v_pk_mul_f32 v[50:51], v[62:63], v[58:59]
	v_add_f32_e32 v58, 1.0, v73
	v_rcp_f32_e32 v56, v34
	v_pk_mul_f32 v[34:35], v[46:47], v[42:43]
	v_add_f32_e32 v42, 1.0, v57
	v_rcp_f32_e32 v40, v18
	v_pk_mul_f32 v[18:19], v[30:31], v[26:27]
	v_add_f32_e32 v26, 1.0, v41
	v_add_f32_e32 v8, 1.0, v8
	v_add_f32_e32 v0, 1.0, v0
	v_add_f32_e32 v9, 1.0, v9
	v_add_f32_e32 v1, 1.0, v1
	v_rcp_f32_e32 v24, v10
	v_add_f32_e32 v3, 1.0, v11
	v_add_f32_e32 v10, 1.0, v25
	v_rcp_f32_e32 v199, v126
	v_rcp_f32_e32 v125, v106
	v_rcp_f32_e32 v105, v90
	v_rcp_f32_e32 v89, v74
	v_rcp_f32_e32 v73, v58
	v_rcp_f32_e32 v57, v42
	v_rcp_f32_e32 v41, v26
	v_rcp_f32_e32 v8, v8
	v_rcp_f32_e32 v0, v0
	v_rcp_f32_e32 v9, v9
	v_rcp_f32_e32 v2, v2
	v_rcp_f32_e32 v3, v3
	v_rcp_f32_e32 v25, v10
	v_rcp_f32_e32 v1, v1
	v_pk_mul_f32 v[116:117], v[128:129], v[116:117]
	v_pk_mul_f32 v[122:123], v[122:123], v[198:199]
	v_pk_mul_f32 v[96:97], v[108:109], v[96:97]
	v_pk_mul_f32 v[102:103], v[102:103], v[124:125]
	v_pk_mul_f32 v[80:81], v[92:93], v[80:81]
	v_pk_mul_f32 v[86:87], v[86:87], v[104:105]
	v_pk_mul_f32 v[64:65], v[76:77], v[64:65]
	v_pk_mul_f32 v[70:71], v[70:71], v[88:89]
	v_pk_mul_f32 v[48:49], v[60:61], v[48:49]
	v_pk_mul_f32 v[54:55], v[54:55], v[72:73]
	v_pk_mul_f32 v[32:33], v[44:45], v[32:33]
	v_pk_mul_f32 v[38:39], v[38:39], v[56:57]
	v_pk_mul_f32 v[16:17], v[28:29], v[16:17]
	v_pk_mul_f32 v[22:23], v[22:23], v[40:41]
	v_pk_mul_f32 v[10:11], v[14:15], v[2:3]
	v_pk_mul_f32 v[8:9], v[12:13], v[8:9]
	v_pk_mul_f32 v[2:3], v[6:7], v[24:25]
	v_pk_mul_f32 v[0:1], v[4:5], v[0:1]
	s_waitcnt vmcnt(7)
; __device__ __forceinline__ float bf_lo(unsigned w) { return __uint_as_float(w << 16); }
; __device__ __forceinline__ float bf_hi(unsigned w) { return __uint_as_float(w & 0xffff0000u); }
; __device__ __forceinline__ u32x4 pack8(const f32x4 a, const f32x4 b) { u32x4 w; w.x = cvt_pk_bf16(a[0], a[1]); w.y = cvt_pk_bf16(a[2], a[3]); w.z = cvt_pk_bf16(b[0], b[1]); w.w = cvt_pk_bf16(b[2], b[3]); return w; }
; #define PG8_BAR __builtin_amdgcn_s_barrier()
;     __device__ __forceinline__ void operator()(const f32x4 (&acc)[2][2][4][2], const Unit& u, int wr, int wc, int fr, int fq) const {
;     ...
; #pragma unroll
;         for (int ai = 0; ai < 2; ++ai)
; #pragma unroll
;             for (int m = 0; m < 4; ++m) { const int row = row0 + ai * HALF + m * 16; const u32x4 s = sg[ai][m];
;                 const f32x4 s0 = (f32x4){bf_lo(s.x), bf_hi(s.x), bf_lo(s.y), bf_hi(s.y)}, s1 = (f32x4){bf_lo(s.z), bf_hi(s.z), bf_lo(s.w), bf_hi(s.w)};
;                 *(u32x4*)(mix + (size_t)row * 2048 + 1024 + colg) = pack8(t[ai][m][0] * s0, t[ai][m][1] * s1); }
; template <class Epi, class Sched, bool ALIGN_EPI = false, bool SP2 = false>
; __device__ __forceinline__ void gemm_phase(PG8_LAS unsigned char* lds, const Gemm g, const Sched& S, const Epi& E, const int wave_id) {
;     ...
;         if constexpr (!Epi::AFTER_DRAIN) { E(acc, cur, wr, wc, fr, fq); S.done(cur); }
;         if (!has_next) break;
; #pragma unroll
;         for (int a = 0; a < 2; ++a)
; #pragma unroll
;             for (int b = 0; b < 2; ++b)
; #pragma unroll
;                 for (int m = 0; m < 4; ++m)
; #pragma unroll
;                     for (int n = 0; n < 2; ++n) acc[a][b][m][n] = (f32x4){0.f, 0.f, 0.f, 0.f};
;         cur = nxt; cA = nA; cB = nB; ++ui;
;         if constexpr (ALIGN_EPI) { if (wr == 1) PG8_BAR; }
	v_lshlrev_b32_e32 v4, 16, v156
	v_and_b32_e32 v5, 0xffff0000, v156
	v_lshlrev_b32_e32 v6, 16, v157
	v_and_b32_e32 v7, 0xffff0000, v157
	v_lshlrev_b32_e32 v12, 16, v158
	v_and_b32_e32 v13, 0xffff0000, v158
	v_lshlrev_b32_e32 v14, 16, v159
	v_pk_mul_f32 v[6:7], v[118:119], v[6:7]
	v_pk_mul_f32 v[4:5], v[116:117], v[4:5]
	v_pk_mul_f32 v[12:13], v[120:121], v[12:13]
	v_and_b32_e32 v15, 0xffff0000, v159
	v_cvt_pk_bf16_f32 v4, v4, v5
	v_cvt_pk_bf16_f32 v5, v6, v7
	v_cvt_pk_bf16_f32 v6, v12, v13
	v_lshlrev_b64 v[12:13], 12, v[190:191]
	v_pk_mul_f32 v[14:15], v[122:123], v[14:15]
	v_lshl_add_u64 v[12:13], v[170:171], 0, v[12:13]
	v_cvt_pk_bf16_f32 v7, v14, v15
	global_store_dwordx4 v[12:13], v[4:7], off offset:2048
	s_waitcnt vmcnt(7)
	v_lshlrev_b32_e32 v12, 16, v154
	v_and_b32_e32 v13, 0xffff0000, v154
	v_lshlrev_b32_e32 v4, 16, v152
	v_and_b32_e32 v5, 0xffff0000, v152
	v_lshlrev_b32_e32 v6, 16, v153
	v_and_b32_e32 v7, 0xffff0000, v153
	v_pk_mul_f32 v[6:7], v[98:99], v[6:7]
	v_pk_mul_f32 v[4:5], v[96:97], v[4:5]
	v_pk_mul_f32 v[12:13], v[100:101], v[12:13]
	v_lshlrev_b32_e32 v14, 16, v155
	v_and_b32_e32 v15, 0xffff0000, v155
	v_cvt_pk_bf16_f32 v4, v4, v5
	v_cvt_pk_bf16_f32 v5, v6, v7
	v_cvt_pk_bf16_f32 v6, v12, v13
	v_lshlrev_b64 v[12:13], 12, v[188:189]
	v_pk_mul_f32 v[14:15], v[102:103], v[14:15]
	v_lshl_add_u64 v[12:13], v[170:171], 0, v[12:13]
	v_cvt_pk_bf16_f32 v7, v14, v15
	global_store_dwordx4 v[12:13], v[4:7], off offset:2048
	s_waitcnt vmcnt(7)
	v_lshlrev_b32_e32 v12, 16, v150
	v_and_b32_e32 v13, 0xffff0000, v150
	v_lshlrev_b32_e32 v4, 16, v148
	v_and_b32_e32 v5, 0xffff0000, v148
	v_lshlrev_b32_e32 v6, 16, v149
	v_and_b32_e32 v7, 0xffff0000, v149
	v_pk_mul_f32 v[6:7], v[82:83], v[6:7]
	v_pk_mul_f32 v[4:5], v[80:81], v[4:5]
	v_pk_mul_f32 v[12:13], v[84:85], v[12:13]
	v_lshlrev_b32_e32 v14, 16, v151
	v_and_b32_e32 v15, 0xffff0000, v151
	v_cvt_pk_bf16_f32 v4, v4, v5
	v_cvt_pk_bf16_f32 v5, v6, v7
	v_cvt_pk_bf16_f32 v6, v12, v13
	v_lshlrev_b64 v[12:13], 12, v[186:187]
	v_pk_mul_f32 v[14:15], v[86:87], v[14:15]
	v_lshl_add_u64 v[12:13], v[170:171], 0, v[12:13]
	v_cvt_pk_bf16_f32 v7, v14, v15
	global_store_dwordx4 v[12:13], v[4:7], off offset:2048
	s_waitcnt vmcnt(7)
	v_lshlrev_b32_e32 v12, 16, v146
	v_and_b32_e32 v13, 0xffff0000, v146
	v_lshlrev_b32_e32 v4, 16, v144
	v_and_b32_e32 v5, 0xffff0000, v144
	v_lshlrev_b32_e32 v6, 16, v145
	v_and_b32_e32 v7, 0xffff0000, v145
	v_pk_mul_f32 v[6:7], v[66:67], v[6:7]
	v_pk_mul_f32 v[4:5], v[64:65], v[4:5]
	v_pk_mul_f32 v[12:13], v[68:69], v[12:13]
	v_lshlrev_b32_e32 v14, 16, v147
	v_and_b32_e32 v15, 0xffff0000, v147
	v_cvt_pk_bf16_f32 v4, v4, v5
	v_cvt_pk_bf16_f32 v5, v6, v7
	v_cvt_pk_bf16_f32 v6, v12, v13
	v_lshlrev_b64 v[12:13], 12, v[184:185]
	v_pk_mul_f32 v[14:15], v[70:71], v[14:15]
	v_lshl_add_u64 v[12:13], v[170:171], 0, v[12:13]
	v_cvt_pk_bf16_f32 v7, v14, v15
	global_store_dwordx4 v[12:13], v[4:7], off offset:2048
	s_waitcnt vmcnt(7)
	v_lshlrev_b32_e32 v12, 16, v142
	v_and_b32_e32 v13, 0xffff0000, v142
	v_lshlrev_b32_e32 v4, 16, v140
	v_and_b32_e32 v5, 0xffff0000, v140
	v_lshlrev_b32_e32 v6, 16, v141
	v_and_b32_e32 v7, 0xffff0000, v141
	v_pk_mul_f32 v[6:7], v[50:51], v[6:7]
	v_pk_mul_f32 v[4:5], v[48:49], v[4:5]
	v_pk_mul_f32 v[12:13], v[52:53], v[12:13]
	v_lshlrev_b32_e32 v14, 16, v143
	v_and_b32_e32 v15, 0xffff0000, v143
	v_cvt_pk_bf16_f32 v4, v4, v5
	v_cvt_pk_bf16_f32 v5, v6, v7
	v_cvt_pk_bf16_f32 v6, v12, v13
	v_lshlrev_b64 v[12:13], 12, v[182:183]
	v_pk_mul_f32 v[14:15], v[54:55], v[14:15]
	v_lshl_add_u64 v[12:13], v[170:171], 0, v[12:13]
	v_cvt_pk_bf16_f32 v7, v14, v15
	global_store_dwordx4 v[12:13], v[4:7], off offset:2048
	s_waitcnt vmcnt(7)
	v_lshlrev_b32_e32 v12, 16, v138
	v_and_b32_e32 v13, 0xffff0000, v138
	v_lshlrev_b32_e32 v4, 16, v136
	v_and_b32_e32 v5, 0xffff0000, v136
	v_lshlrev_b32_e32 v6, 16, v137
	v_and_b32_e32 v7, 0xffff0000, v137
	v_pk_mul_f32 v[6:7], v[34:35], v[6:7]
	v_pk_mul_f32 v[4:5], v[32:33], v[4:5]
	v_pk_mul_f32 v[12:13], v[36:37], v[12:13]
	v_lshlrev_b32_e32 v14, 16, v139
	v_and_b32_e32 v15, 0xffff0000, v139
	v_cvt_pk_bf16_f32 v4, v4, v5
	v_cvt_pk_bf16_f32 v5, v6, v7
	v_cvt_pk_bf16_f32 v6, v12, v13
	v_lshlrev_b64 v[12:13], 12, v[180:181]
	v_pk_mul_f32 v[14:15], v[38:39], v[14:15]
	v_lshl_add_u64 v[12:13], v[170:171], 0, v[12:13]
	v_cvt_pk_bf16_f32 v7, v14, v15
	global_store_dwordx4 v[12:13], v[4:7], off offset:2048
	s_waitcnt vmcnt(7)
	v_lshlrev_b32_e32 v12, 16, v134
	v_and_b32_e32 v13, 0xffff0000, v134
	v_lshlrev_b32_e32 v4, 16, v132
	v_and_b32_e32 v5, 0xffff0000, v132
	v_lshlrev_b32_e32 v6, 16, v133
	v_and_b32_e32 v7, 0xffff0000, v133
	v_pk_mul_f32 v[6:7], v[18:19], v[6:7]
	v_pk_mul_f32 v[4:5], v[16:17], v[4:5]
	v_pk_mul_f32 v[12:13], v[20:21], v[12:13]
	v_cvt_pk_bf16_f32 v4, v4, v5
	v_cvt_pk_bf16_f32 v5, v6, v7
	v_lshlrev_b32_e32 v14, 16, v135
	v_cvt_pk_bf16_f32 v6, v12, v13
	v_lshlrev_b64 v[12:13], 12, v[178:179]
	v_and_b32_e32 v15, 0xffff0000, v135
	v_lshl_add_u64 v[12:13], v[170:171], 0, v[12:13]
	v_pk_mul_f32 v[14:15], v[22:23], v[14:15]
	s_andn2_b64 vcc, exec, s[20:21]
	v_cvt_pk_bf16_f32 v7, v14, v15
	global_store_dwordx4 v[12:13], v[4:7], off offset:2048
	s_waitcnt vmcnt(7)
	v_lshlrev_b32_e32 v12, 16, v114
	v_and_b32_e32 v13, 0xffff0000, v114
	v_lshlrev_b32_e32 v4, 16, v112
	v_and_b32_e32 v5, 0xffff0000, v112
	v_lshlrev_b32_e32 v14, 16, v115
	v_and_b32_e32 v15, 0xffff0000, v115
	v_pk_mul_f32 v[4:5], v[8:9], v[4:5]
	v_pk_mul_f32 v[8:9], v[2:3], v[14:15]
	v_pk_mul_f32 v[2:3], v[0:1], v[12:13]
	v_cvt_pk_bf16_f32 v0, v4, v5
	v_lshlrev_b64 v[4:5], 12, v[176:177]
	v_lshlrev_b32_e32 v6, 16, v113
	v_and_b32_e32 v7, 0xffff0000, v113
	v_lshl_add_u64 v[4:5], v[170:171], 0, v[4:5]
	s_mov_b64 s[20:21], -1
	v_pk_mul_f32 v[6:7], v[10:11], v[6:7]
	s_nop 0
	v_cvt_pk_bf16_f32 v1, v6, v7
	v_cvt_pk_bf16_f32 v2, v2, v3
	v_cvt_pk_bf16_f32 v3, v8, v9
	global_store_dwordx4 v[4:5], v[0:3], off offset:2048
	s_cbranch_vccnz .LBB0_448
	s_andn2_b64 vcc, exec, s[2:3]
	s_cbranch_vccnz .LBB0_447
	s_barrier
	s_branch .LBB0_447

; __device__ __forceinline__ float bf_lo(unsigned w) { return __uint_as_float(w << 16); }
; __device__ __forceinline__ float bf_hi(unsigned w) { return __uint_as_float(w & 0xffff0000u); }
; __device__ __forceinline__ u32x4 pack8(const f32x4 a, const f32x4 b) { u32x4 w; w.x = cvt_pk_bf16(a[0], a[1]); w.y = cvt_pk_bf16(a[2], a[3]); w.z = cvt_pk_bf16(b[0], b[1]); w.w = cvt_pk_bf16(b[2], b[3]); return w; }
; __device__ __forceinline__ u32x4 ldnt(const bf16_t* p) { return __builtin_nontemporal_load((const u32x4*)p); }
;     __device__ __forceinline__ void operator()(const f32x4 (&acc)[2][2][4][2], const Unit& u, int wr, int wc, int fr, int fq) const {
;     ...
;             for (int m = 0; m < 4; ++m) ri[ai][m] = rinv[row0 + ai * HALF + m * 16];
; #pragma unroll
;         for (int ai = 0; ai < 2; ++ai)
; #pragma unroll
;             for (int m = 0; m < 4; ++m)
; #pragma unroll
;                 for (int bj = 0; bj < 2; ++bj) xv[ai][m][bj] = ldnt(xb + (size_t)(row0 + ai * HALF + m * 16) * 2048 + col0 + bj * HALF);
;         asm volatile("" ::: "memory");
; #pragma unroll
;         for (int ai = 0; ai < 2; ++ai)
; #pragma unroll
;             for (int m = 0; m < 4; ++m) { const size_t rb = (size_t)(row0 + ai * HALF + m * 16) * 2048 + col0;
; #pragma unroll
;                 for (int bj = 0; bj < 2; ++bj) { const u32x4 x4 = xv[ai][m][bj];
;                     const f32x4 h0 = (f32x4){bf_lo(x4.x), bf_hi(x4.x), bf_lo(x4.y), bf_hi(x4.y)} * ri[ai][m] + acc[ai][bj][m][0], h1 = (f32x4){bf_lo(x4.z), bf_hi(x4.z), bf_lo(x4.w), bf_hi(x4.w)} * ri[ai][m] + acc[ai][bj][m][1];
;                     *(u32x4*)(hb + rb + bj * HALF) = pack8(h0, h1); } }
.LBB0_525:
	v_lshl_add_u32 v128, s1, 8, v189
	v_ashrrev_i32_e32 v129, 31, v128
	v_lshlrev_b64 v[130:131], 12, v[128:129]
	v_lshl_add_u64 v[132:133], v[178:179], 0, v[130:131]
	v_or_b32_e32 v134, 16, v128
	global_load_dwordx4 v[210:213], v[132:133], off nt
	global_load_dwordx4 v[214:217], v[132:133], off offset:256 nt
	v_lshl_add_u64 v[132:133], v[128:129], 2, s[42:43]
	v_ashrrev_i32_e32 v135, 31, v134
	global_load_dword v234, v[132:133], off
	global_load_dword v238, v[132:133], off offset:64
	v_lshlrev_b64 v[236:237], 12, v[134:135]
	v_lshl_add_u64 v[134:135], v[178:179], 0, v[236:237]
	global_load_dwordx4 v[218:221], v[134:135], off nt
	global_load_dwordx4 v[222:225], v[134:135], off offset:256 nt
	global_load_dword v204, v[132:133], off offset:128
	global_load_dword v200, v[132:133], off offset:192
	global_load_dword v196, v[132:133], off offset:512
	global_load_dword v192, v[132:133], off offset:576
	global_load_dword v188, v[132:133], off offset:640
	global_load_dword v176, v[132:133], off offset:704
	v_or_b32_e32 v136, 32, v128
	v_or_b32_e32 v128, 48, v128
	s_mov_b64 s[46:47], 0x90000
	s_mov_b64 s[48:49], 0xa0000
	v_ashrrev_i32_e32 v137, 31, v136
	v_ashrrev_i32_e32 v129, 31, v128
	s_mov_b64 s[50:51], 0xb0000
	v_lshl_add_u64 v[198:199], v[130:131], 0, s[36:37]
	v_lshl_add_u64 v[194:195], v[130:131], 0, s[46:47]
	v_lshl_add_u64 v[190:191], v[130:131], 0, s[48:49]
	v_lshlrev_b64 v[206:207], 12, v[136:137]
	v_lshlrev_b64 v[202:203], 12, v[128:129]
	v_lshl_add_u64 v[186:187], v[130:131], 0, s[50:51]
	v_lshl_add_u64 v[240:241], v[180:181], 0, v[130:131]
	v_lshl_add_u64 v[128:129], v[178:179], 0, v[206:207]
	v_lshl_add_u64 v[130:131], v[178:179], 0, v[202:203]
	v_lshl_add_u64 v[132:133], v[178:179], 0, v[198:199]
	v_lshl_add_u64 v[134:135], v[178:179], 0, v[194:195]
	v_lshl_add_u64 v[136:137], v[178:179], 0, v[190:191]
	v_lshl_add_u64 v[242:243], v[178:179], 0, v[186:187]
	global_load_dwordx4 v[226:229], v[128:129], off nt
	global_load_dwordx4 v[230:233], v[128:129], off offset:256 nt
	global_load_dwordx4 v[164:167], v[130:131], off nt
	global_load_dwordx4 v[160:163], v[130:131], off offset:256 nt
	global_load_dwordx4 v[156:159], v[132:133], off nt
	global_load_dwordx4 v[152:155], v[132:133], off offset:256 nt
	global_load_dwordx4 v[148:151], v[134:135], off nt
	global_load_dwordx4 v[144:147], v[134:135], off offset:256 nt
	global_load_dwordx4 v[140:143], v[136:137], off nt
	s_nop 0
	global_load_dwordx4 v[136:139], v[136:137], off offset:256 nt
	s_nop 0
	global_load_dwordx4 v[132:135], v[242:243], off nt
	global_load_dwordx4 v[128:131], v[242:243], off offset:256 nt
	s_andn2_b64 vcc, exec, s[10:11]
	s_mov_b64 s[10:11], -1
	s_waitcnt vmcnt(23)
	v_lshlrev_b32_e32 v242, 16, v210
	v_and_b32_e32 v243, 0xffff0000, v210
	v_lshlrev_b32_e32 v210, 16, v211
	v_and_b32_e32 v211, 0xffff0000, v211
	v_lshlrev_b32_e32 v246, 16, v212
	v_and_b32_e32 v247, 0xffff0000, v212
	v_lshlrev_b32_e32 v212, 16, v213
	v_and_b32_e32 v213, 0xffff0000, v213
	s_waitcnt vmcnt(22)
	v_lshlrev_b32_e32 v250, 16, v216
	v_and_b32_e32 v251, 0xffff0000, v216
	v_lshlrev_b32_e32 v216, 16, v217
	v_and_b32_e32 v217, 0xffff0000, v217
	v_lshlrev_b32_e32 v248, 16, v214
	v_and_b32_e32 v249, 0xffff0000, v214
	v_lshlrev_b32_e32 v214, 16, v215
	v_and_b32_e32 v215, 0xffff0000, v215
	s_waitcnt vmcnt(21)
	v_pk_fma_f32 v[126:127], v[234:235], v[210:211], v[126:127] op_sel_hi:[0,1,1]
	v_pk_fma_f32 v[124:125], v[234:235], v[242:243], v[124:125] op_sel_hi:[0,1,1]
	v_pk_fma_f32 v[122:123], v[234:235], v[212:213], v[122:123] op_sel_hi:[0,1,1]
	v_pk_fma_f32 v[120:121], v[234:235], v[246:247], v[120:121] op_sel_hi:[0,1,1]
	v_pk_fma_f32 v[210:211], v[234:235], v[216:217], v[114:115] op_sel_hi:[0,1,1]
	v_pk_fma_f32 v[212:213], v[234:235], v[250:251], v[112:113] op_sel_hi:[0,1,1]
	v_cvt_pk_bf16_f32 v112, v124, v125
	v_cvt_pk_bf16_f32 v113, v126, v127
	v_cvt_pk_bf16_f32 v114, v120, v121
	v_cvt_pk_bf16_f32 v115, v122, v123
	v_pk_fma_f32 v[118:119], v[234:235], v[214:215], v[118:119] op_sel_hi:[0,1,1]
	v_pk_fma_f32 v[116:117], v[234:235], v[248:249], v[116:117] op_sel_hi:[0,1,1]
	global_store_dwordx4 v[240:241], v[112:115], off
	s_waitcnt vmcnt(20)
	v_lshlrev_b32_e32 v214, 16, v218
	v_and_b32_e32 v215, 0xffff0000, v218
	v_cvt_pk_bf16_f32 v112, v116, v117
	v_cvt_pk_bf16_f32 v113, v118, v119
	v_cvt_pk_bf16_f32 v114, v212, v213
	v_cvt_pk_bf16_f32 v115, v210, v211
	global_store_dwordx4 v[240:241], v[112:115], off offset:256
	v_lshlrev_b32_e32 v216, 16, v219
	v_and_b32_e32 v217, 0xffff0000, v219
	v_lshlrev_b32_e32 v112, 16, v220
	v_and_b32_e32 v113, 0xffff0000, v220
	v_lshlrev_b32_e32 v114, 16, v221
	v_and_b32_e32 v115, 0xffff0000, v221
	v_pk_fma_f32 v[108:109], v[238:239], v[214:215], v[108:109] op_sel_hi:[0,1,1]
	v_pk_fma_f32 v[114:115], v[238:239], v[114:115], v[106:107] op_sel_hi:[0,1,1]
	v_pk_fma_f32 v[106:107], v[238:239], v[112:113], v[104:105] op_sel_hi:[0,1,1]
	v_pk_fma_f32 v[110:111], v[238:239], v[216:217], v[110:111] op_sel_hi:[0,1,1]
	v_cvt_pk_bf16_f32 v104, v108, v109
	v_cvt_pk_bf16_f32 v105, v110, v111
	v_cvt_pk_bf16_f32 v106, v106, v107
	v_cvt_pk_bf16_f32 v107, v114, v115
	v_lshl_add_u64 v[108:109], v[180:181], 0, v[236:237]
	global_store_dwordx4 v[108:109], v[104:107], off
	s_nop 1
	s_waitcnt vmcnt(21)
; __device__ __forceinline__ float bf_lo(unsigned w) { return __uint_as_float(w << 16); }
; __device__ __forceinline__ float bf_hi(unsigned w) { return __uint_as_float(w & 0xffff0000u); }
; __device__ __forceinline__ u32x4 pack8(const f32x4 a, const f32x4 b) { u32x4 w; w.x = cvt_pk_bf16(a[0], a[1]); w.y = cvt_pk_bf16(a[2], a[3]); w.z = cvt_pk_bf16(b[0], b[1]); w.w = cvt_pk_bf16(b[2], b[3]); return w; }
;     __device__ __forceinline__ void operator()(const f32x4 (&acc)[2][2][4][2], const Unit& u, int wr, int wc, int fr, int fq) const {
;     ...
;             for (int m = 0; m < 4; ++m) { const size_t rb = (size_t)(row0 + ai * HALF + m * 16) * 2048 + col0;
; #pragma unroll
;                 for (int bj = 0; bj < 2; ++bj) { const u32x4 x4 = xv[ai][m][bj];
;                     const f32x4 h0 = (f32x4){bf_lo(x4.x), bf_hi(x4.x), bf_lo(x4.y), bf_hi(x4.y)} * ri[ai][m] + acc[ai][bj][m][0], h1 = (f32x4){bf_lo(x4.z), bf_hi(x4.z), bf_lo(x4.w), bf_hi(x4.w)} * ri[ai][m] + acc[ai][bj][m][1];
;                     *(u32x4*)(hb + rb + bj * HALF) = pack8(h0, h1); } }
	v_lshlrev_b32_e32 v104, 16, v222
	v_and_b32_e32 v105, 0xffff0000, v222
	v_lshlrev_b32_e32 v106, 16, v223
	v_and_b32_e32 v107, 0xffff0000, v223
	v_pk_fma_f32 v[102:103], v[238:239], v[106:107], v[102:103] op_sel_hi:[0,1,1]
	v_pk_fma_f32 v[100:101], v[238:239], v[104:105], v[100:101] op_sel_hi:[0,1,1]
	v_lshlrev_b32_e32 v104, 16, v224
	v_and_b32_e32 v105, 0xffff0000, v224
	v_lshlrev_b32_e32 v106, 16, v225
	v_and_b32_e32 v107, 0xffff0000, v225
	v_pk_fma_f32 v[106:107], v[238:239], v[106:107], v[98:99] op_sel_hi:[0,1,1]
	v_pk_fma_f32 v[98:99], v[238:239], v[104:105], v[96:97] op_sel_hi:[0,1,1]
	v_cvt_pk_bf16_f32 v96, v100, v101
	v_cvt_pk_bf16_f32 v97, v102, v103
	v_cvt_pk_bf16_f32 v98, v98, v99
	v_cvt_pk_bf16_f32 v99, v106, v107
	global_store_dwordx4 v[108:109], v[96:99], off offset:256
	s_nop 1
	s_waitcnt vmcnt(15)
	v_lshlrev_b32_e32 v96, 16, v226
	v_and_b32_e32 v97, 0xffff0000, v226
	v_lshlrev_b32_e32 v98, 16, v227
	v_and_b32_e32 v99, 0xffff0000, v227
	v_pk_fma_f32 v[94:95], v[204:205], v[98:99], v[94:95] op_sel_hi:[0,1,1]
	v_pk_fma_f32 v[92:93], v[204:205], v[96:97], v[92:93] op_sel_hi:[0,1,1]
	v_lshlrev_b32_e32 v96, 16, v228
	v_and_b32_e32 v97, 0xffff0000, v228
	v_lshlrev_b32_e32 v98, 16, v229
	v_and_b32_e32 v99, 0xffff0000, v229
	v_pk_fma_f32 v[98:99], v[204:205], v[98:99], v[90:91] op_sel_hi:[0,1,1]
	v_pk_fma_f32 v[90:91], v[204:205], v[96:97], v[88:89] op_sel_hi:[0,1,1]
	v_cvt_pk_bf16_f32 v88, v92, v93
	v_cvt_pk_bf16_f32 v89, v94, v95
	v_cvt_pk_bf16_f32 v90, v90, v91
	v_cvt_pk_bf16_f32 v91, v98, v99
	v_lshl_add_u64 v[92:93], v[180:181], 0, v[206:207]
	global_store_dwordx4 v[92:93], v[88:91], off
	s_nop 1
	s_waitcnt vmcnt(15)
	v_lshlrev_b32_e32 v88, 16, v230
	v_and_b32_e32 v89, 0xffff0000, v230
	v_lshlrev_b32_e32 v90, 16, v231
	v_and_b32_e32 v91, 0xffff0000, v231
	v_pk_fma_f32 v[86:87], v[204:205], v[90:91], v[86:87] op_sel_hi:[0,1,1]
	v_pk_fma_f32 v[84:85], v[204:205], v[88:89], v[84:85] op_sel_hi:[0,1,1]
	v_lshlrev_b32_e32 v88, 16, v232
	v_and_b32_e32 v89, 0xffff0000, v232
	v_lshlrev_b32_e32 v90, 16, v233
	v_and_b32_e32 v91, 0xffff0000, v233
	v_pk_fma_f32 v[90:91], v[204:205], v[90:91], v[82:83] op_sel_hi:[0,1,1]
	v_pk_fma_f32 v[82:83], v[204:205], v[88:89], v[80:81] op_sel_hi:[0,1,1]
	v_cvt_pk_bf16_f32 v80, v84, v85
	v_cvt_pk_bf16_f32 v81, v86, v87
	v_cvt_pk_bf16_f32 v82, v82, v83
	v_cvt_pk_bf16_f32 v83, v90, v91
	global_store_dwordx4 v[92:93], v[80:83], off offset:256
	s_nop 1
	s_waitcnt vmcnt(15)
	v_lshlrev_b32_e32 v80, 16, v164
	v_and_b32_e32 v81, 0xffff0000, v164
	v_lshlrev_b32_e32 v82, 16, v165
	v_and_b32_e32 v83, 0xffff0000, v165
	v_pk_fma_f32 v[78:79], v[200:201], v[82:83], v[78:79] op_sel_hi:[0,1,1]
	v_pk_fma_f32 v[76:77], v[200:201], v[80:81], v[76:77] op_sel_hi:[0,1,1]
	v_lshlrev_b32_e32 v80, 16, v166
	v_and_b32_e32 v81, 0xffff0000, v166
	v_lshlrev_b32_e32 v82, 16, v167
	v_and_b32_e32 v83, 0xffff0000, v167
	v_pk_fma_f32 v[82:83], v[200:201], v[82:83], v[74:75] op_sel_hi:[0,1,1]
	v_pk_fma_f32 v[74:75], v[200:201], v[80:81], v[72:73] op_sel_hi:[0,1,1]
	v_cvt_pk_bf16_f32 v72, v76, v77
	v_cvt_pk_bf16_f32 v73, v78, v79
	v_cvt_pk_bf16_f32 v74, v74, v75
	v_cvt_pk_bf16_f32 v75, v82, v83
	v_lshl_add_u64 v[76:77], v[180:181], 0, v[202:203]
	global_store_dwordx4 v[76:77], v[72:75], off
	s_nop 1
	s_waitcnt vmcnt(15)
	v_lshlrev_b32_e32 v72, 16, v160
	v_and_b32_e32 v73, 0xffff0000, v160
	v_lshlrev_b32_e32 v74, 16, v161
	v_and_b32_e32 v75, 0xffff0000, v161
	v_pk_fma_f32 v[70:71], v[200:201], v[74:75], v[70:71] op_sel_hi:[0,1,1]
	v_pk_fma_f32 v[68:69], v[200:201], v[72:73], v[68:69] op_sel_hi:[0,1,1]
	v_lshlrev_b32_e32 v72, 16, v162
	v_and_b32_e32 v73, 0xffff0000, v162
	v_lshlrev_b32_e32 v74, 16, v163
	v_and_b32_e32 v75, 0xffff0000, v163
	v_pk_fma_f32 v[74:75], v[200:201], v[74:75], v[66:67] op_sel_hi:[0,1,1]
	v_pk_fma_f32 v[66:67], v[200:201], v[72:73], v[64:65] op_sel_hi:[0,1,1]
	v_cvt_pk_bf16_f32 v64, v68, v69
	v_cvt_pk_bf16_f32 v65, v70, v71
	v_cvt_pk_bf16_f32 v66, v66, v67
	v_cvt_pk_bf16_f32 v67, v74, v75
	global_store_dwordx4 v[76:77], v[64:67], off offset:256
	s_nop 1
	s_waitcnt vmcnt(15)
	v_lshlrev_b32_e32 v64, 16, v156
	v_and_b32_e32 v65, 0xffff0000, v156
	v_lshlrev_b32_e32 v66, 16, v157
	v_and_b32_e32 v67, 0xffff0000, v157
	v_pk_fma_f32 v[62:63], v[196:197], v[66:67], v[62:63] op_sel_hi:[0,1,1]
	v_pk_fma_f32 v[60:61], v[196:197], v[64:65], v[60:61] op_sel_hi:[0,1,1]
	v_lshlrev_b32_e32 v64, 16, v158
	v_and_b32_e32 v65, 0xffff0000, v158
	v_lshlrev_b32_e32 v66, 16, v159
	v_and_b32_e32 v67, 0xffff0000, v159
	v_pk_fma_f32 v[66:67], v[196:197], v[66:67], v[58:59] op_sel_hi:[0,1,1]
	v_pk_fma_f32 v[58:59], v[196:197], v[64:65], v[56:57] op_sel_hi:[0,1,1]
	v_cvt_pk_bf16_f32 v56, v60, v61
	v_cvt_pk_bf16_f32 v57, v62, v63
	v_cvt_pk_bf16_f32 v58, v58, v59
	v_cvt_pk_bf16_f32 v59, v66, v67
	v_lshl_add_u64 v[60:61], v[180:181], 0, v[198:199]
	global_store_dwordx4 v[60:61], v[56:59], off
	s_nop 1
	s_waitcnt vmcnt(15)
	v_lshlrev_b32_e32 v56, 16, v152
	v_and_b32_e32 v57, 0xffff0000, v152
	v_lshlrev_b32_e32 v58, 16, v153
	v_and_b32_e32 v59, 0xffff0000, v153
	v_pk_fma_f32 v[54:55], v[196:197], v[58:59], v[54:55] op_sel_hi:[0,1,1]
	v_pk_fma_f32 v[52:53], v[196:197], v[56:57], v[52:53] op_sel_hi:[0,1,1]
	v_lshlrev_b32_e32 v56, 16, v154
	v_and_b32_e32 v57, 0xffff0000, v154
	v_lshlrev_b32_e32 v58, 16, v155
	v_and_b32_e32 v59, 0xffff0000, v155
	v_pk_fma_f32 v[58:59], v[196:197], v[58:59], v[50:51] op_sel_hi:[0,1,1]
	v_pk_fma_f32 v[50:51], v[196:197], v[56:57], v[48:49] op_sel_hi:[0,1,1]
	v_cvt_pk_bf16_f32 v48, v52, v53
	v_cvt_pk_bf16_f32 v49, v54, v55
	v_cvt_pk_bf16_f32 v50, v50, v51
	v_cvt_pk_bf16_f32 v51, v58, v59
	global_store_dwordx4 v[60:61], v[48:51], off offset:256
	s_nop 1
	s_waitcnt vmcnt(15)
; __device__ __forceinline__ float bf_lo(unsigned w) { return __uint_as_float(w << 16); }
; __device__ __forceinline__ float bf_hi(unsigned w) { return __uint_as_float(w & 0xffff0000u); }
; __device__ __forceinline__ u32x4 pack8(const f32x4 a, const f32x4 b) { u32x4 w; w.x = cvt_pk_bf16(a[0], a[1]); w.y = cvt_pk_bf16(a[2], a[3]); w.z = cvt_pk_bf16(b[0], b[1]); w.w = cvt_pk_bf16(b[2], b[3]); return w; }
; #define PG8_BAR __builtin_amdgcn_s_barrier()
;     __device__ __forceinline__ void operator()(const f32x4 (&acc)[2][2][4][2], const Unit& u, int wr, int wc, int fr, int fq) const {
;     ...
;             for (int m = 0; m < 4; ++m) { const size_t rb = (size_t)(row0 + ai * HALF + m * 16) * 2048 + col0;
; #pragma unroll
;                 for (int bj = 0; bj < 2; ++bj) { const u32x4 x4 = xv[ai][m][bj];
;                     const f32x4 h0 = (f32x4){bf_lo(x4.x), bf_hi(x4.x), bf_lo(x4.y), bf_hi(x4.y)} * ri[ai][m] + acc[ai][bj][m][0], h1 = (f32x4){bf_lo(x4.z), bf_hi(x4.z), bf_lo(x4.w), bf_hi(x4.w)} * ri[ai][m] + acc[ai][bj][m][1];
;                     *(u32x4*)(hb + rb + bj * HALF) = pack8(h0, h1); } }
; template <class Epi, class Sched, bool ALIGN_EPI = false, bool SP2 = false>
; __device__ __forceinline__ void gemm_phase(PG8_LAS unsigned char* lds, const Gemm g, const Sched& S, const Epi& E, const int wave_id) {
;     ...
;         if (!has_next) break;
; #pragma unroll
;         for (int a = 0; a < 2; ++a)
; #pragma unroll
;             for (int b = 0; b < 2; ++b)
; #pragma unroll
;                 for (int m = 0; m < 4; ++m)
; #pragma unroll
;                     for (int n = 0; n < 2; ++n) acc[a][b][m][n] = (f32x4){0.f, 0.f, 0.f, 0.f};
;         cur = nxt; cA = nA; cB = nB; ++ui;
;         if constexpr (ALIGN_EPI) { if (wr == 1) PG8_BAR; }
	v_lshlrev_b32_e32 v48, 16, v148
	v_and_b32_e32 v49, 0xffff0000, v148
	v_lshlrev_b32_e32 v50, 16, v149
	v_and_b32_e32 v51, 0xffff0000, v149
	v_pk_fma_f32 v[46:47], v[192:193], v[50:51], v[46:47] op_sel_hi:[0,1,1]
	v_pk_fma_f32 v[44:45], v[192:193], v[48:49], v[44:45] op_sel_hi:[0,1,1]
	v_lshlrev_b32_e32 v48, 16, v150
	v_and_b32_e32 v49, 0xffff0000, v150
	v_lshlrev_b32_e32 v50, 16, v151
	v_and_b32_e32 v51, 0xffff0000, v151
	v_pk_fma_f32 v[50:51], v[192:193], v[50:51], v[42:43] op_sel_hi:[0,1,1]
	v_pk_fma_f32 v[42:43], v[192:193], v[48:49], v[40:41] op_sel_hi:[0,1,1]
	v_cvt_pk_bf16_f32 v40, v44, v45
	v_cvt_pk_bf16_f32 v41, v46, v47
	v_cvt_pk_bf16_f32 v42, v42, v43
	v_cvt_pk_bf16_f32 v43, v50, v51
	v_lshl_add_u64 v[44:45], v[180:181], 0, v[194:195]
	global_store_dwordx4 v[44:45], v[40:43], off
	s_nop 1
	s_waitcnt vmcnt(15)
	v_lshlrev_b32_e32 v40, 16, v144
	v_and_b32_e32 v41, 0xffff0000, v144
	v_lshlrev_b32_e32 v42, 16, v145
	v_and_b32_e32 v43, 0xffff0000, v145
	v_pk_fma_f32 v[38:39], v[192:193], v[42:43], v[38:39] op_sel_hi:[0,1,1]
	v_pk_fma_f32 v[36:37], v[192:193], v[40:41], v[36:37] op_sel_hi:[0,1,1]
	v_lshlrev_b32_e32 v40, 16, v146
	v_and_b32_e32 v41, 0xffff0000, v146
	v_lshlrev_b32_e32 v42, 16, v147
	v_and_b32_e32 v43, 0xffff0000, v147
	v_pk_fma_f32 v[42:43], v[192:193], v[42:43], v[34:35] op_sel_hi:[0,1,1]
	v_pk_fma_f32 v[34:35], v[192:193], v[40:41], v[32:33] op_sel_hi:[0,1,1]
	v_cvt_pk_bf16_f32 v32, v36, v37
	v_cvt_pk_bf16_f32 v33, v38, v39
	v_cvt_pk_bf16_f32 v34, v34, v35
	v_cvt_pk_bf16_f32 v35, v42, v43
	global_store_dwordx4 v[44:45], v[32:35], off offset:256
	s_nop 1
	s_waitcnt vmcnt(15)
	v_lshlrev_b32_e32 v32, 16, v140
	v_and_b32_e32 v33, 0xffff0000, v140
	v_lshlrev_b32_e32 v34, 16, v141
	v_and_b32_e32 v35, 0xffff0000, v141
	v_pk_fma_f32 v[30:31], v[188:189], v[34:35], v[30:31] op_sel_hi:[0,1,1]
	v_pk_fma_f32 v[28:29], v[188:189], v[32:33], v[28:29] op_sel_hi:[0,1,1]
	v_lshlrev_b32_e32 v32, 16, v142
	v_and_b32_e32 v33, 0xffff0000, v142
	v_lshlrev_b32_e32 v34, 16, v143
	v_and_b32_e32 v35, 0xffff0000, v143
	v_pk_fma_f32 v[34:35], v[188:189], v[34:35], v[26:27] op_sel_hi:[0,1,1]
	v_pk_fma_f32 v[26:27], v[188:189], v[32:33], v[24:25] op_sel_hi:[0,1,1]
	v_cvt_pk_bf16_f32 v24, v28, v29
	v_cvt_pk_bf16_f32 v25, v30, v31
	v_cvt_pk_bf16_f32 v26, v26, v27
	v_cvt_pk_bf16_f32 v27, v34, v35
	v_lshl_add_u64 v[28:29], v[180:181], 0, v[190:191]
	global_store_dwordx4 v[28:29], v[24:27], off
	s_nop 1
	s_waitcnt vmcnt(15)
	v_lshlrev_b32_e32 v24, 16, v136
	v_and_b32_e32 v25, 0xffff0000, v136
	v_lshlrev_b32_e32 v26, 16, v137
	v_and_b32_e32 v27, 0xffff0000, v137
	v_pk_fma_f32 v[22:23], v[188:189], v[26:27], v[22:23] op_sel_hi:[0,1,1]
	v_pk_fma_f32 v[20:21], v[188:189], v[24:25], v[20:21] op_sel_hi:[0,1,1]
	v_lshlrev_b32_e32 v24, 16, v138
	v_and_b32_e32 v25, 0xffff0000, v138
	v_lshlrev_b32_e32 v26, 16, v139
	v_and_b32_e32 v27, 0xffff0000, v139
	v_pk_fma_f32 v[26:27], v[188:189], v[26:27], v[18:19] op_sel_hi:[0,1,1]
	v_pk_fma_f32 v[18:19], v[188:189], v[24:25], v[16:17] op_sel_hi:[0,1,1]
	v_cvt_pk_bf16_f32 v16, v20, v21
	v_cvt_pk_bf16_f32 v17, v22, v23
	v_cvt_pk_bf16_f32 v18, v18, v19
	v_cvt_pk_bf16_f32 v19, v26, v27
	global_store_dwordx4 v[28:29], v[16:19], off offset:256
	s_nop 1
	s_waitcnt vmcnt(15)
	v_lshlrev_b32_e32 v16, 16, v132
	v_and_b32_e32 v17, 0xffff0000, v132
	v_lshlrev_b32_e32 v18, 16, v133
	v_and_b32_e32 v19, 0xffff0000, v133
	v_pk_fma_f32 v[14:15], v[176:177], v[18:19], v[14:15] op_sel_hi:[0,1,1]
	v_pk_fma_f32 v[12:13], v[176:177], v[16:17], v[12:13] op_sel_hi:[0,1,1]
	v_lshlrev_b32_e32 v16, 16, v134
	v_and_b32_e32 v17, 0xffff0000, v134
	v_lshlrev_b32_e32 v18, 16, v135
	v_and_b32_e32 v19, 0xffff0000, v135
	v_pk_fma_f32 v[18:19], v[176:177], v[18:19], v[10:11] op_sel_hi:[0,1,1]
	v_pk_fma_f32 v[10:11], v[176:177], v[16:17], v[8:9] op_sel_hi:[0,1,1]
	v_cvt_pk_bf16_f32 v8, v12, v13
	v_cvt_pk_bf16_f32 v9, v14, v15
	v_cvt_pk_bf16_f32 v10, v10, v11
	v_cvt_pk_bf16_f32 v11, v18, v19
	v_lshl_add_u64 v[12:13], v[180:181], 0, v[186:187]
	global_store_dwordx4 v[12:13], v[8:11], off
	s_nop 1
	s_waitcnt vmcnt(15)
	v_lshlrev_b32_e32 v8, 16, v128
	v_and_b32_e32 v9, 0xffff0000, v128
	v_lshlrev_b32_e32 v10, 16, v129
	v_and_b32_e32 v11, 0xffff0000, v129
	v_pk_fma_f32 v[6:7], v[176:177], v[10:11], v[6:7] op_sel_hi:[0,1,1]
	v_pk_fma_f32 v[4:5], v[176:177], v[8:9], v[4:5] op_sel_hi:[0,1,1]
	v_lshlrev_b32_e32 v8, 16, v130
	v_and_b32_e32 v9, 0xffff0000, v130
	v_lshlrev_b32_e32 v10, 16, v131
	v_and_b32_e32 v11, 0xffff0000, v131
	v_pk_fma_f32 v[10:11], v[176:177], v[10:11], v[2:3] op_sel_hi:[0,1,1]
	v_pk_fma_f32 v[2:3], v[176:177], v[8:9], v[0:1] op_sel_hi:[0,1,1]
	v_cvt_pk_bf16_f32 v0, v4, v5
	v_cvt_pk_bf16_f32 v1, v6, v7
	v_cvt_pk_bf16_f32 v2, v2, v3
	v_cvt_pk_bf16_f32 v3, v10, v11
	global_store_dwordx4 v[12:13], v[0:3], off offset:256
	s_cbranch_vccnz .LBB0_520
	s_and_b64 vcc, exec, s[8:9]
	s_cbranch_vccnz .LBB0_519
	s_barrier
	s_branch .LBB0_519
